# attention work queues: a workgroup whose own queue is exhausted reads the other seven heads together and stops at once when all are exhausted
# speedup vs baseline: 1.0803x; 1.0025x over previous
.LBB0_479:
	s_cmp_lg_u32 s3, 1
	s_cbranch_scc1 .Lqs_go
	s_add_i32 s8, s33, 1
	s_and_b32 s8, s8, 7
	s_lshl_b32 s8, s8, 6
	v_mov_b32_e32 v249, s8
	global_load_dword v249, v249, s[84:85] sc1
	s_add_i32 s8, s33, 2
	s_and_b32 s8, s8, 7
	s_lshl_b32 s8, s8, 6
	v_mov_b32_e32 v250, s8
	global_load_dword v250, v250, s[84:85] sc1
	s_add_i32 s8, s33, 3
	s_and_b32 s8, s8, 7
	s_lshl_b32 s8, s8, 6
	v_mov_b32_e32 v251, s8
	global_load_dword v251, v251, s[84:85] sc1
	s_add_i32 s8, s33, 4
	s_and_b32 s8, s8, 7
	s_lshl_b32 s8, s8, 6
	v_mov_b32_e32 v252, s8
	global_load_dword v252, v252, s[84:85] sc1
	s_add_i32 s8, s33, 5
	s_and_b32 s8, s8, 7
	s_lshl_b32 s8, s8, 6
	v_mov_b32_e32 v253, s8
	global_load_dword v253, v253, s[84:85] sc1
	s_add_i32 s8, s33, 6
	s_and_b32 s8, s8, 7
	s_lshl_b32 s8, s8, 6
	v_mov_b32_e32 v254, s8
	global_load_dword v254, v254, s[84:85] sc1
	s_add_i32 s8, s33, 7
	s_and_b32 s8, s8, 7
	s_lshl_b32 s8, s8, 6
	v_mov_b32_e32 v255, s8
	global_load_dword v255, v255, s[84:85] sc1
	s_waitcnt vmcnt(0)
	v_min_u32_e32 v249, v249, v250
	v_min_u32_e32 v251, v251, v252
	v_min_u32_e32 v253, v253, v254
	v_min_u32_e32 v249, v249, v255
	v_min_u32_e32 v251, v251, v253
	v_min_u32_e32 v249, v249, v251
	s_movk_i32 s14, 0x8b
	v_cmp_lt_u32_e32 vcc, s14, v249
	v_mov_b32_e32 v1, -1
	s_cbranch_vccnz .LBB0_482
